# in/up GEMM K loops: loop-carried pointer updates and exit compare moved in front of the last segment's barrier, next-address selects moved behind the head segment's LDS reads
# baseline (speedup 1.0000x reference)
.LBB0_301:
	s_add_i32 s12, 0, 0x10000
	s_add_i32 s13, 0, 0x14000
	v_add_u32_e32 v158, s12, v147
	v_add_u32_e32 v174, s13, v147
	ds_read_b128 v[142:145], v158
	ds_read_b128 v[150:153], v158 offset:1024
	ds_read_b128 v[154:157], v158 offset:2048
	ds_read_b128 v[158:161], v158 offset:3072
	ds_read_b128 v[162:165], v174
	ds_read_b128 v[166:169], v174 offset:1024
	ds_read_b128 v[170:173], v174 offset:2048
	ds_read_b128 v[174:177], v174 offset:3072
	v_lshl_add_u64 v[194:195], s[54:55], 0, v[138:139]
	s_add_i32 m0, s59, 0xc000
	ds_read_b128 v[178:181], v149
	ds_read_b128 v[182:185], v149 offset:1024
	ds_read_b128 v[186:189], v149 offset:2048
	ds_read_b128 v[190:193], v149 offset:3072
	ds_read_b128 v[208:211], v149 offset:4096
	ds_read_b128 v[212:215], v149 offset:5120
	ds_read_b128 v[216:219], v149 offset:6144
	ds_read_b128 v[220:223], v149 offset:7168
	s_add_u32 s10, s54, 0xfff80080
	s_addc_u32 s11, s55, -1
	s_cmp_eq_u32 s73, 28
	s_cselect_b32 s57, s45, s11
	s_cselect_b32 s56, s69, s10
	s_cselect_b32 s21, s43, s72
	s_cselect_b32 s20, s70, s71
	global_load_lds_dwordx4 v[194:195], off
	v_lshl_add_u64 v[194:195], s[54:55], 0, v[140:141]
	s_add_i32 m0, s59, 0xe000
	s_nop 0
	global_load_lds_dwordx4 v[194:195], off
	s_waitcnt vmcnt(8)
	s_waitcnt lgkmcnt(0)
	s_barrier
	s_setprio 1
	s_waitcnt lgkmcnt(0)
	v_mfma_f32_16x16x32_bf16 v[128:131], v[142:145], v[178:181], v[128:131]
	v_mfma_f32_16x16x32_bf16 v[124:127], v[154:157], v[178:181], v[124:127]
	v_mfma_f32_16x16x32_bf16 v[120:123], v[142:145], v[186:189], v[120:123]
	v_mfma_f32_16x16x32_bf16 v[112:115], v[154:157], v[186:189], v[112:115]
	v_mfma_f32_16x16x32_bf16 v[104:107], v[142:145], v[208:211], v[104:107]
	v_mfma_f32_16x16x32_bf16 v[94:97], v[154:157], v[208:211], v[94:97]
	v_mfma_f32_16x16x32_bf16 v[86:89], v[142:145], v[216:219], v[86:89]
	v_mfma_f32_16x16x32_bf16 v[78:81], v[154:157], v[216:219], v[78:81]
	v_mfma_f32_16x16x32_bf16 v[128:131], v[150:153], v[182:185], v[128:131]
	v_mfma_f32_16x16x32_bf16 v[124:127], v[158:161], v[182:185], v[124:127]
	v_mfma_f32_16x16x32_bf16 v[120:123], v[150:153], v[190:193], v[120:123]
	v_mfma_f32_16x16x32_bf16 v[112:115], v[158:161], v[190:193], v[112:115]
	v_mfma_f32_16x16x32_bf16 v[104:107], v[150:153], v[212:215], v[104:107]
	v_mfma_f32_16x16x32_bf16 v[94:97], v[158:161], v[212:215], v[94:97]
	v_mfma_f32_16x16x32_bf16 v[86:89], v[150:153], v[220:223], v[86:89]
	v_mfma_f32_16x16x32_bf16 v[78:81], v[158:161], v[220:223], v[78:81]
	s_setprio 0
	s_setprio 1
	v_mfma_f32_16x16x32_bf16 v[116:119], v[162:165], v[178:181], v[116:119]
	v_mfma_f32_16x16x32_bf16 v[108:111], v[170:173], v[178:181], v[108:111]
	v_mfma_f32_16x16x32_bf16 v[100:103], v[162:165], v[186:189], v[100:103]
	v_mfma_f32_16x16x32_bf16 v[90:93], v[170:173], v[186:189], v[90:93]
	v_mfma_f32_16x16x32_bf16 v[82:85], v[162:165], v[208:211], v[82:85]
	v_mfma_f32_16x16x32_bf16 v[74:77], v[170:173], v[208:211], v[74:77]
	v_mfma_f32_16x16x32_bf16 v[70:73], v[162:165], v[216:219], v[70:73]
	v_mfma_f32_16x16x32_bf16 v[66:69], v[170:173], v[216:219], v[66:69]
	v_mfma_f32_16x16x32_bf16 v[116:119], v[166:169], v[182:185], v[116:119]
	v_mfma_f32_16x16x32_bf16 v[108:111], v[174:177], v[182:185], v[108:111]
	v_mfma_f32_16x16x32_bf16 v[100:103], v[166:169], v[190:193], v[100:103]
	v_mfma_f32_16x16x32_bf16 v[90:93], v[174:177], v[190:193], v[90:93]
	v_mfma_f32_16x16x32_bf16 v[82:85], v[166:169], v[212:215], v[82:85]
	v_mfma_f32_16x16x32_bf16 v[74:77], v[174:177], v[212:215], v[74:77]
	v_mfma_f32_16x16x32_bf16 v[70:73], v[166:169], v[220:223], v[70:73]
	v_mfma_f32_16x16x32_bf16 v[66:69], v[174:177], v[220:223], v[66:69]
	s_setprio 0
	s_barrier
	s_add_i32 s10, s12, s58
	v_lshl_add_u64 v[194:195], s[20:21], 0, v[136:137]
	s_mov_b32 m0, s10
	ds_read_b128 v[178:181], v149 offset:16384
	ds_read_b128 v[182:185], v149 offset:17408
	ds_read_b128 v[186:189], v149 offset:18432
	ds_read_b128 v[190:193], v149 offset:19456
	ds_read_b128 v[208:211], v149 offset:20480
	ds_read_b128 v[212:215], v149 offset:21504
	ds_read_b128 v[216:219], v149 offset:22528
	ds_read_b128 v[220:223], v149 offset:23552
	global_load_lds_dwordx4 v[194:195], off
	s_add_i32 m0, s10, 0x2000
	s_add_u32 s10, s20, 0x4000
	v_lshl_add_u64 v[194:195], s[20:21], 0, v[132:133]
	s_addc_u32 s11, s21, 0
	s_add_i32 s12, s13, s58
	global_load_lds_dwordx4 v[194:195], off
	v_lshl_add_u64 v[194:195], s[10:11], 0, v[136:137]
	s_mov_b32 m0, s12
	v_lshl_add_u64 v[196:197], s[56:57], 0, v[134:135]
	global_load_lds_dwordx4 v[194:195], off
	v_lshl_add_u64 v[194:195], s[10:11], 0, v[132:133]
	s_add_i32 m0, s12, 0x2000
	s_nop 0
	global_load_lds_dwordx4 v[194:195], off
	v_lshl_add_u64 v[194:195], s[56:57], 0, v[98:99]
	s_mov_b32 m0, s59
	s_nop 0
	global_load_lds_dwordx4 v[194:195], off
	s_mov_b32 m0, s60
	s_nop 0
	global_load_lds_dwordx4 v[196:197], off
	s_waitcnt vmcnt(8)
	s_waitcnt lgkmcnt(0)
	s_barrier
	s_setprio 1
	s_waitcnt lgkmcnt(0)
	v_mfma_f32_16x16x32_bf16 v[62:65], v[142:145], v[178:181], v[62:65]
	v_mfma_f32_16x16x32_bf16 v[58:61], v[154:157], v[178:181], v[58:61]
	v_mfma_f32_16x16x32_bf16 v[54:57], v[142:145], v[186:189], v[54:57]
	v_mfma_f32_16x16x32_bf16 v[46:49], v[154:157], v[186:189], v[46:49]
	v_mfma_f32_16x16x32_bf16 v[38:41], v[142:145], v[208:211], v[38:41]
	v_mfma_f32_16x16x32_bf16 v[30:33], v[154:157], v[208:211], v[30:33]
	v_mfma_f32_16x16x32_bf16 v[22:25], v[142:145], v[216:219], v[22:25]
	v_mfma_f32_16x16x32_bf16 v[14:17], v[154:157], v[216:219], v[14:17]
	v_mfma_f32_16x16x32_bf16 v[62:65], v[150:153], v[182:185], v[62:65]
	v_mfma_f32_16x16x32_bf16 v[58:61], v[158:161], v[182:185], v[58:61]
	v_mfma_f32_16x16x32_bf16 v[54:57], v[150:153], v[190:193], v[54:57]
	v_mfma_f32_16x16x32_bf16 v[46:49], v[158:161], v[190:193], v[46:49]
	v_mfma_f32_16x16x32_bf16 v[38:41], v[150:153], v[212:215], v[38:41]
	v_mfma_f32_16x16x32_bf16 v[30:33], v[158:161], v[212:215], v[30:33]
	v_mfma_f32_16x16x32_bf16 v[22:25], v[150:153], v[220:223], v[22:25]
	v_mfma_f32_16x16x32_bf16 v[14:17], v[158:161], v[220:223], v[14:17]
	s_setprio 0
	s_setprio 1
	v_mfma_f32_16x16x32_bf16 v[50:53], v[162:165], v[178:181], v[50:53]
	v_mfma_f32_16x16x32_bf16 v[42:45], v[170:173], v[178:181], v[42:45]
	v_mfma_f32_16x16x32_bf16 v[34:37], v[162:165], v[186:189], v[34:37]
	v_mfma_f32_16x16x32_bf16 v[26:29], v[170:173], v[186:189], v[26:29]
	v_mfma_f32_16x16x32_bf16 v[18:21], v[162:165], v[208:211], v[18:21]
	v_mfma_f32_16x16x32_bf16 v[10:13], v[170:173], v[208:211], v[10:13]
	v_mfma_f32_16x16x32_bf16 v[6:9], v[162:165], v[216:219], v[6:9]
	v_mfma_f32_16x16x32_bf16 v[2:5], v[170:173], v[216:219], v[2:5]
	v_mfma_f32_16x16x32_bf16 v[50:53], v[166:169], v[182:185], v[50:53]
	v_mfma_f32_16x16x32_bf16 v[42:45], v[174:177], v[182:185], v[42:45]
	v_mfma_f32_16x16x32_bf16 v[34:37], v[166:169], v[190:193], v[34:37]
	v_mfma_f32_16x16x32_bf16 v[26:29], v[174:177], v[190:193], v[26:29]
	v_mfma_f32_16x16x32_bf16 v[18:21], v[166:169], v[212:215], v[18:21]
	v_mfma_f32_16x16x32_bf16 v[10:13], v[174:177], v[212:215], v[10:13]
	v_mfma_f32_16x16x32_bf16 v[6:9], v[166:169], v[220:223], v[6:9]
	v_mfma_f32_16x16x32_bf16 v[2:5], v[174:177], v[220:223], v[2:5]
	s_setprio 0
	s_barrier
	s_add_i32 s12, 0, 0x18000
	s_add_i32 s13, 0, 0x1c000
	v_add_u32_e32 v158, s12, v147
	v_add_u32_e32 v174, s13, v147
	ds_read_b128 v[142:145], v158
	ds_read_b128 v[150:153], v158 offset:1024
	ds_read_b128 v[154:157], v158 offset:2048
	ds_read_b128 v[158:161], v158 offset:3072
	ds_read_b128 v[162:165], v174
	ds_read_b128 v[166:169], v174 offset:1024
	ds_read_b128 v[170:173], v174 offset:2048
	ds_read_b128 v[174:177], v174 offset:3072
	s_add_u32 s10, s56, 0x80000
	s_addc_u32 s11, s57, 0
	s_mov_b32 m0, s61
	v_lshl_add_u64 v[198:199], s[10:11], 0, v[98:99]
	ds_read_b128 v[178:181], v149 offset:32768
	ds_read_b128 v[182:185], v149 offset:33792
	ds_read_b128 v[186:189], v149 offset:34816
	ds_read_b128 v[190:193], v149 offset:35840
	ds_read_b128 v[208:211], v149 offset:36864
	ds_read_b128 v[212:215], v149 offset:37888
	ds_read_b128 v[216:219], v149 offset:38912
	ds_read_b128 v[220:223], v149 offset:39936
	global_load_lds_dwordx4 v[198:199], off
	v_lshl_add_u64 v[198:199], s[10:11], 0, v[134:135]
	s_mov_b32 m0, s62
	s_nop 0
	global_load_lds_dwordx4 v[198:199], off
	s_waitcnt vmcnt(8)
	s_waitcnt lgkmcnt(0)
	s_barrier
	s_setprio 1
	s_waitcnt lgkmcnt(0)
	v_mfma_f32_16x16x32_bf16 v[128:131], v[142:145], v[178:181], v[128:131]
	v_mfma_f32_16x16x32_bf16 v[124:127], v[154:157], v[178:181], v[124:127]
	v_mfma_f32_16x16x32_bf16 v[120:123], v[142:145], v[186:189], v[120:123]
	v_mfma_f32_16x16x32_bf16 v[112:115], v[154:157], v[186:189], v[112:115]
	v_mfma_f32_16x16x32_bf16 v[104:107], v[142:145], v[208:211], v[104:107]
	v_mfma_f32_16x16x32_bf16 v[94:97], v[154:157], v[208:211], v[94:97]
	v_mfma_f32_16x16x32_bf16 v[86:89], v[142:145], v[216:219], v[86:89]
	v_mfma_f32_16x16x32_bf16 v[78:81], v[154:157], v[216:219], v[78:81]
	v_mfma_f32_16x16x32_bf16 v[128:131], v[150:153], v[182:185], v[128:131]
	v_mfma_f32_16x16x32_bf16 v[124:127], v[158:161], v[182:185], v[124:127]
	v_mfma_f32_16x16x32_bf16 v[120:123], v[150:153], v[190:193], v[120:123]
	v_mfma_f32_16x16x32_bf16 v[112:115], v[158:161], v[190:193], v[112:115]
	v_mfma_f32_16x16x32_bf16 v[104:107], v[150:153], v[212:215], v[104:107]
	v_mfma_f32_16x16x32_bf16 v[94:97], v[158:161], v[212:215], v[94:97]
	v_mfma_f32_16x16x32_bf16 v[86:89], v[150:153], v[220:223], v[86:89]
	v_mfma_f32_16x16x32_bf16 v[78:81], v[158:161], v[220:223], v[78:81]
	s_setprio 0
	s_setprio 1
	v_mfma_f32_16x16x32_bf16 v[116:119], v[162:165], v[178:181], v[116:119]
	v_mfma_f32_16x16x32_bf16 v[108:111], v[170:173], v[178:181], v[108:111]
	v_mfma_f32_16x16x32_bf16 v[100:103], v[162:165], v[186:189], v[100:103]
	v_mfma_f32_16x16x32_bf16 v[90:93], v[170:173], v[186:189], v[90:93]
	v_mfma_f32_16x16x32_bf16 v[82:85], v[162:165], v[208:211], v[82:85]
	v_mfma_f32_16x16x32_bf16 v[74:77], v[170:173], v[208:211], v[74:77]
	v_mfma_f32_16x16x32_bf16 v[70:73], v[162:165], v[216:219], v[70:73]
	v_mfma_f32_16x16x32_bf16 v[66:69], v[170:173], v[216:219], v[66:69]
	v_mfma_f32_16x16x32_bf16 v[116:119], v[166:169], v[182:185], v[116:119]
	v_mfma_f32_16x16x32_bf16 v[108:111], v[174:177], v[182:185], v[108:111]
	v_mfma_f32_16x16x32_bf16 v[100:103], v[166:169], v[190:193], v[100:103]
	v_mfma_f32_16x16x32_bf16 v[90:93], v[174:177], v[190:193], v[90:93]
	v_mfma_f32_16x16x32_bf16 v[82:85], v[166:169], v[212:215], v[82:85]
	v_mfma_f32_16x16x32_bf16 v[74:77], v[174:177], v[212:215], v[74:77]
	v_mfma_f32_16x16x32_bf16 v[70:73], v[166:169], v[220:223], v[70:73]
	v_mfma_f32_16x16x32_bf16 v[66:69], v[174:177], v[220:223], v[66:69]
	s_setprio 0
	s_barrier
	s_add_u32 s10, s20, 0x8000
	s_addc_u32 s11, s21, 0
	s_add_i32 s12, s12, s58
	v_lshl_add_u64 v[198:199], s[10:11], 0, v[136:137]
	s_mov_b32 m0, s12
	ds_read_b128 v[178:181], v149 offset:49152
	ds_read_b128 v[182:185], v149 offset:50176
	ds_read_b128 v[186:189], v149 offset:51200
	ds_read_b128 v[190:193], v149 offset:52224
	ds_read_b128 v[208:211], v149 offset:53248
	ds_read_b128 v[212:215], v149 offset:54272
	ds_read_b128 v[216:219], v149 offset:55296
	ds_read_b128 v[220:223], v149 offset:56320
	global_load_lds_dwordx4 v[198:199], off
	s_add_i32 m0, s12, 0x2000
	v_lshl_add_u64 v[198:199], s[10:11], 0, v[132:133]
	s_add_u32 s10, s20, 0xc000
	s_addc_u32 s11, s21, 0
	s_add_i32 s12, s13, s58
	global_load_lds_dwordx4 v[198:199], off
	v_lshl_add_u64 v[198:199], s[10:11], 0, v[136:137]
	s_mov_b32 m0, s12
	v_lshl_add_u64 v[194:195], v[194:195], 0, s[24:25]
	global_load_lds_dwordx4 v[198:199], off
	v_lshl_add_u64 v[198:199], s[10:11], 0, v[132:133]
	s_add_i32 m0, s12, 0x2000
	s_nop 0
	global_load_lds_dwordx4 v[198:199], off
	s_mov_b32 m0, s63
	s_nop 0
	global_load_lds_dwordx4 v[194:195], off
	v_lshl_add_u64 v[194:195], v[196:197], 0, s[24:25]
	s_mov_b32 m0, s64
	s_nop 0
	global_load_lds_dwordx4 v[194:195], off
	s_waitcnt vmcnt(8)
	s_waitcnt lgkmcnt(0)
	s_barrier
	s_setprio 1
	s_waitcnt lgkmcnt(0)
	v_mfma_f32_16x16x32_bf16 v[62:65], v[142:145], v[178:181], v[62:65]
	v_mfma_f32_16x16x32_bf16 v[58:61], v[154:157], v[178:181], v[58:61]
	v_mfma_f32_16x16x32_bf16 v[54:57], v[142:145], v[186:189], v[54:57]
	v_mfma_f32_16x16x32_bf16 v[46:49], v[154:157], v[186:189], v[46:49]
	v_mfma_f32_16x16x32_bf16 v[38:41], v[142:145], v[208:211], v[38:41]
	v_mfma_f32_16x16x32_bf16 v[30:33], v[154:157], v[208:211], v[30:33]
	v_mfma_f32_16x16x32_bf16 v[22:25], v[142:145], v[216:219], v[22:25]
	v_mfma_f32_16x16x32_bf16 v[14:17], v[154:157], v[216:219], v[14:17]
	v_mfma_f32_16x16x32_bf16 v[62:65], v[150:153], v[182:185], v[62:65]
	v_mfma_f32_16x16x32_bf16 v[58:61], v[158:161], v[182:185], v[58:61]
	v_mfma_f32_16x16x32_bf16 v[54:57], v[150:153], v[190:193], v[54:57]
	v_mfma_f32_16x16x32_bf16 v[46:49], v[158:161], v[190:193], v[46:49]
	v_mfma_f32_16x16x32_bf16 v[38:41], v[150:153], v[212:215], v[38:41]
	v_mfma_f32_16x16x32_bf16 v[30:33], v[158:161], v[212:215], v[30:33]
	v_mfma_f32_16x16x32_bf16 v[22:25], v[150:153], v[220:223], v[22:25]
	v_mfma_f32_16x16x32_bf16 v[14:17], v[158:161], v[220:223], v[14:17]
	s_setprio 0
	s_setprio 1
	v_mfma_f32_16x16x32_bf16 v[50:53], v[162:165], v[178:181], v[50:53]
	v_mfma_f32_16x16x32_bf16 v[42:45], v[170:173], v[178:181], v[42:45]
	v_mfma_f32_16x16x32_bf16 v[34:37], v[162:165], v[186:189], v[34:37]
	v_mfma_f32_16x16x32_bf16 v[26:29], v[170:173], v[186:189], v[26:29]
	v_mfma_f32_16x16x32_bf16 v[18:21], v[162:165], v[208:211], v[18:21]
	v_mfma_f32_16x16x32_bf16 v[10:13], v[170:173], v[208:211], v[10:13]
	v_mfma_f32_16x16x32_bf16 v[6:9], v[162:165], v[216:219], v[6:9]
	v_mfma_f32_16x16x32_bf16 v[2:5], v[170:173], v[216:219], v[2:5]
	v_mfma_f32_16x16x32_bf16 v[50:53], v[166:169], v[182:185], v[50:53]
	v_mfma_f32_16x16x32_bf16 v[42:45], v[174:177], v[182:185], v[42:45]
	v_mfma_f32_16x16x32_bf16 v[34:37], v[166:169], v[190:193], v[34:37]
	v_mfma_f32_16x16x32_bf16 v[26:29], v[174:177], v[190:193], v[26:29]
	v_mfma_f32_16x16x32_bf16 v[18:21], v[166:169], v[212:215], v[18:21]
	v_mfma_f32_16x16x32_bf16 v[10:13], v[174:177], v[212:215], v[10:13]
	v_mfma_f32_16x16x32_bf16 v[6:9], v[166:169], v[220:223], v[6:9]
	v_mfma_f32_16x16x32_bf16 v[2:5], v[174:177], v[220:223], v[2:5]
	s_add_i32 s73, s73, 2
	s_add_u32 s71, s71, 0x10000
	s_addc_u32 s72, s72, 0
	s_add_u32 s54, s54, 0x100
	s_addc_u32 s55, s55, 0
	s_cmp_gt_u32 s73, 29
	s_setprio 0
	s_barrier
	s_cbranch_scc0 .LBB0_301

.Lgi_h0_loop:
	s_add_i32 s12, 0, 0x10000
	s_add_i32 s13, 0, 0x14000
	v_add_u32_e32 v158, s12, v147
	v_add_u32_e32 v174, s13, v147
	ds_read_b128 v[142:145], v158
	ds_read_b128 v[150:153], v158 offset:1024
	ds_read_b128 v[154:157], v158 offset:2048
	ds_read_b128 v[158:161], v158 offset:3072
	v_lshl_add_u64 v[194:195], s[54:55], 0, v[138:139]
	s_add_i32 m0, s59, 0xc000
	ds_read_b128 v[178:181], v149
	ds_read_b128 v[182:185], v149 offset:1024
	ds_read_b128 v[186:189], v149 offset:2048
	ds_read_b128 v[190:193], v149 offset:3072
	ds_read_b128 v[208:211], v149 offset:4096
	ds_read_b128 v[212:215], v149 offset:5120
	ds_read_b128 v[216:219], v149 offset:6144
	ds_read_b128 v[220:223], v149 offset:7168
	s_add_u32 s10, s54, 0xfff80080
	s_addc_u32 s11, s55, -1
	s_cmp_eq_u32 s73, 28
	s_cselect_b32 s57, s45, s11
	s_cselect_b32 s56, s69, s10
	s_cselect_b32 s21, s43, s72
	s_cselect_b32 s20, s70, s71
	global_load_lds_dwordx4 v[194:195], off
	v_lshl_add_u64 v[194:195], s[54:55], 0, v[140:141]
	s_add_i32 m0, s59, 0xe000
	s_nop 0
	global_load_lds_dwordx4 v[194:195], off
	s_waitcnt vmcnt(8)
	s_waitcnt lgkmcnt(0)
	s_barrier
	s_setprio 1
	s_waitcnt lgkmcnt(0)
	v_mfma_f32_16x16x32_bf16 v[128:131], v[142:145], v[178:181], v[128:131]
	v_mfma_f32_16x16x32_bf16 v[124:127], v[154:157], v[178:181], v[124:127]
	v_mfma_f32_16x16x32_bf16 v[120:123], v[142:145], v[186:189], v[120:123]
	v_mfma_f32_16x16x32_bf16 v[112:115], v[154:157], v[186:189], v[112:115]
	v_mfma_f32_16x16x32_bf16 v[104:107], v[142:145], v[208:211], v[104:107]
	v_mfma_f32_16x16x32_bf16 v[94:97], v[154:157], v[208:211], v[94:97]
	v_mfma_f32_16x16x32_bf16 v[86:89], v[142:145], v[216:219], v[86:89]
	v_mfma_f32_16x16x32_bf16 v[78:81], v[154:157], v[216:219], v[78:81]
	v_mfma_f32_16x16x32_bf16 v[128:131], v[150:153], v[182:185], v[128:131]
	v_mfma_f32_16x16x32_bf16 v[124:127], v[158:161], v[182:185], v[124:127]
	v_mfma_f32_16x16x32_bf16 v[120:123], v[150:153], v[190:193], v[120:123]
	v_mfma_f32_16x16x32_bf16 v[112:115], v[158:161], v[190:193], v[112:115]
	v_mfma_f32_16x16x32_bf16 v[104:107], v[150:153], v[212:215], v[104:107]
	v_mfma_f32_16x16x32_bf16 v[94:97], v[158:161], v[212:215], v[94:97]
	v_mfma_f32_16x16x32_bf16 v[86:89], v[150:153], v[220:223], v[86:89]
	v_mfma_f32_16x16x32_bf16 v[78:81], v[158:161], v[220:223], v[78:81]
	s_setprio 0
	s_setprio 1
	s_setprio 0
	s_barrier
	s_add_i32 s10, s12, s58
	v_lshl_add_u64 v[194:195], s[20:21], 0, v[136:137]
	s_mov_b32 m0, s10
	ds_read_b128 v[178:181], v149 offset:16384
	ds_read_b128 v[182:185], v149 offset:17408
	ds_read_b128 v[186:189], v149 offset:18432
	ds_read_b128 v[190:193], v149 offset:19456
	ds_read_b128 v[208:211], v149 offset:20480
	ds_read_b128 v[212:215], v149 offset:21504
	ds_read_b128 v[216:219], v149 offset:22528
	ds_read_b128 v[220:223], v149 offset:23552
	global_load_lds_dwordx4 v[194:195], off
	s_add_i32 m0, s10, 0x2000
	s_add_u32 s10, s20, 0x4000
	v_lshl_add_u64 v[194:195], s[20:21], 0, v[132:133]
	s_addc_u32 s11, s21, 0
	s_add_i32 s12, s13, s58
	global_load_lds_dwordx4 v[194:195], off
	v_lshl_add_u64 v[194:195], s[10:11], 0, v[136:137]
	s_mov_b32 m0, s12
	v_lshl_add_u64 v[196:197], s[56:57], 0, v[134:135]
	global_load_lds_dwordx4 v[194:195], off
	v_lshl_add_u64 v[194:195], s[10:11], 0, v[132:133]
	s_add_i32 m0, s12, 0x2000
	s_nop 0
	global_load_lds_dwordx4 v[194:195], off
	v_lshl_add_u64 v[194:195], s[56:57], 0, v[98:99]
	s_mov_b32 m0, s59
	s_nop 0
	global_load_lds_dwordx4 v[194:195], off
	s_mov_b32 m0, s60
	s_nop 0
	global_load_lds_dwordx4 v[196:197], off
	s_waitcnt vmcnt(8)
	s_waitcnt lgkmcnt(0)
	s_barrier
	s_setprio 1
	s_waitcnt lgkmcnt(0)
	v_mfma_f32_16x16x32_bf16 v[62:65], v[142:145], v[178:181], v[62:65]
	v_mfma_f32_16x16x32_bf16 v[58:61], v[154:157], v[178:181], v[58:61]
	v_mfma_f32_16x16x32_bf16 v[54:57], v[142:145], v[186:189], v[54:57]
	v_mfma_f32_16x16x32_bf16 v[46:49], v[154:157], v[186:189], v[46:49]
	v_mfma_f32_16x16x32_bf16 v[38:41], v[142:145], v[208:211], v[38:41]
	v_mfma_f32_16x16x32_bf16 v[30:33], v[154:157], v[208:211], v[30:33]
	v_mfma_f32_16x16x32_bf16 v[22:25], v[142:145], v[216:219], v[22:25]
	v_mfma_f32_16x16x32_bf16 v[14:17], v[154:157], v[216:219], v[14:17]
	v_mfma_f32_16x16x32_bf16 v[62:65], v[150:153], v[182:185], v[62:65]
	v_mfma_f32_16x16x32_bf16 v[58:61], v[158:161], v[182:185], v[58:61]
	v_mfma_f32_16x16x32_bf16 v[54:57], v[150:153], v[190:193], v[54:57]
	v_mfma_f32_16x16x32_bf16 v[46:49], v[158:161], v[190:193], v[46:49]
	v_mfma_f32_16x16x32_bf16 v[38:41], v[150:153], v[212:215], v[38:41]
	v_mfma_f32_16x16x32_bf16 v[30:33], v[158:161], v[212:215], v[30:33]
	v_mfma_f32_16x16x32_bf16 v[22:25], v[150:153], v[220:223], v[22:25]
	v_mfma_f32_16x16x32_bf16 v[14:17], v[158:161], v[220:223], v[14:17]
	s_setprio 0
	s_setprio 1
	s_setprio 0
	s_barrier
	s_add_i32 s12, 0, 0x18000
	s_add_i32 s13, 0, 0x1c000
	v_add_u32_e32 v158, s12, v147
	v_add_u32_e32 v174, s13, v147
	ds_read_b128 v[142:145], v158
	ds_read_b128 v[150:153], v158 offset:1024
	ds_read_b128 v[154:157], v158 offset:2048
	ds_read_b128 v[158:161], v158 offset:3072
	s_add_u32 s10, s56, 0x80000
	s_addc_u32 s11, s57, 0
	s_mov_b32 m0, s61
	v_lshl_add_u64 v[198:199], s[10:11], 0, v[98:99]
	ds_read_b128 v[178:181], v149 offset:32768
	ds_read_b128 v[182:185], v149 offset:33792
	ds_read_b128 v[186:189], v149 offset:34816
	ds_read_b128 v[190:193], v149 offset:35840
	ds_read_b128 v[208:211], v149 offset:36864
	ds_read_b128 v[212:215], v149 offset:37888
	ds_read_b128 v[216:219], v149 offset:38912
	ds_read_b128 v[220:223], v149 offset:39936
	global_load_lds_dwordx4 v[198:199], off
	v_lshl_add_u64 v[198:199], s[10:11], 0, v[134:135]
	s_mov_b32 m0, s62
	s_nop 0
	global_load_lds_dwordx4 v[198:199], off
	s_waitcnt vmcnt(8)
	s_waitcnt lgkmcnt(0)
	s_barrier
	s_setprio 1
	s_waitcnt lgkmcnt(0)
	v_mfma_f32_16x16x32_bf16 v[128:131], v[142:145], v[178:181], v[128:131]
	v_mfma_f32_16x16x32_bf16 v[124:127], v[154:157], v[178:181], v[124:127]
	v_mfma_f32_16x16x32_bf16 v[120:123], v[142:145], v[186:189], v[120:123]
	v_mfma_f32_16x16x32_bf16 v[112:115], v[154:157], v[186:189], v[112:115]
	v_mfma_f32_16x16x32_bf16 v[104:107], v[142:145], v[208:211], v[104:107]
	v_mfma_f32_16x16x32_bf16 v[94:97], v[154:157], v[208:211], v[94:97]
	v_mfma_f32_16x16x32_bf16 v[86:89], v[142:145], v[216:219], v[86:89]
	v_mfma_f32_16x16x32_bf16 v[78:81], v[154:157], v[216:219], v[78:81]
	v_mfma_f32_16x16x32_bf16 v[128:131], v[150:153], v[182:185], v[128:131]
	v_mfma_f32_16x16x32_bf16 v[124:127], v[158:161], v[182:185], v[124:127]
	v_mfma_f32_16x16x32_bf16 v[120:123], v[150:153], v[190:193], v[120:123]
	v_mfma_f32_16x16x32_bf16 v[112:115], v[158:161], v[190:193], v[112:115]
	v_mfma_f32_16x16x32_bf16 v[104:107], v[150:153], v[212:215], v[104:107]
	v_mfma_f32_16x16x32_bf16 v[94:97], v[158:161], v[212:215], v[94:97]
	v_mfma_f32_16x16x32_bf16 v[86:89], v[150:153], v[220:223], v[86:89]
	v_mfma_f32_16x16x32_bf16 v[78:81], v[158:161], v[220:223], v[78:81]
	s_setprio 0
	s_setprio 1
	s_setprio 0
	s_barrier
	s_add_u32 s10, s20, 0x8000
	s_addc_u32 s11, s21, 0
	s_add_i32 s12, s12, s58
	v_lshl_add_u64 v[198:199], s[10:11], 0, v[136:137]
	s_mov_b32 m0, s12
	ds_read_b128 v[178:181], v149 offset:49152
	ds_read_b128 v[182:185], v149 offset:50176
	ds_read_b128 v[186:189], v149 offset:51200
	ds_read_b128 v[190:193], v149 offset:52224
	ds_read_b128 v[208:211], v149 offset:53248
	ds_read_b128 v[212:215], v149 offset:54272
	ds_read_b128 v[216:219], v149 offset:55296
	ds_read_b128 v[220:223], v149 offset:56320
	global_load_lds_dwordx4 v[198:199], off
	s_add_i32 m0, s12, 0x2000
	v_lshl_add_u64 v[198:199], s[10:11], 0, v[132:133]
	s_add_u32 s10, s20, 0xc000
	s_addc_u32 s11, s21, 0
	s_add_i32 s12, s13, s58
	global_load_lds_dwordx4 v[198:199], off
	v_lshl_add_u64 v[198:199], s[10:11], 0, v[136:137]
	s_mov_b32 m0, s12
	v_lshl_add_u64 v[194:195], v[194:195], 0, s[24:25]
	global_load_lds_dwordx4 v[198:199], off
	v_lshl_add_u64 v[198:199], s[10:11], 0, v[132:133]
	s_add_i32 m0, s12, 0x2000
	s_nop 0
	global_load_lds_dwordx4 v[198:199], off
	s_mov_b32 m0, s63
	s_nop 0
	global_load_lds_dwordx4 v[194:195], off
	v_lshl_add_u64 v[194:195], v[196:197], 0, s[24:25]
	s_mov_b32 m0, s64
	s_nop 0
	global_load_lds_dwordx4 v[194:195], off
	s_waitcnt vmcnt(8)
	s_waitcnt lgkmcnt(0)
	s_barrier
	s_setprio 1
	s_waitcnt lgkmcnt(0)
	v_mfma_f32_16x16x32_bf16 v[62:65], v[142:145], v[178:181], v[62:65]
	v_mfma_f32_16x16x32_bf16 v[58:61], v[154:157], v[178:181], v[58:61]
	v_mfma_f32_16x16x32_bf16 v[54:57], v[142:145], v[186:189], v[54:57]
	v_mfma_f32_16x16x32_bf16 v[46:49], v[154:157], v[186:189], v[46:49]
	v_mfma_f32_16x16x32_bf16 v[38:41], v[142:145], v[208:211], v[38:41]
	v_mfma_f32_16x16x32_bf16 v[30:33], v[154:157], v[208:211], v[30:33]
	v_mfma_f32_16x16x32_bf16 v[22:25], v[142:145], v[216:219], v[22:25]
	v_mfma_f32_16x16x32_bf16 v[14:17], v[154:157], v[216:219], v[14:17]
	v_mfma_f32_16x16x32_bf16 v[62:65], v[150:153], v[182:185], v[62:65]
	v_mfma_f32_16x16x32_bf16 v[58:61], v[158:161], v[182:185], v[58:61]
	v_mfma_f32_16x16x32_bf16 v[54:57], v[150:153], v[190:193], v[54:57]
	v_mfma_f32_16x16x32_bf16 v[46:49], v[158:161], v[190:193], v[46:49]
	v_mfma_f32_16x16x32_bf16 v[38:41], v[150:153], v[212:215], v[38:41]
	v_mfma_f32_16x16x32_bf16 v[30:33], v[158:161], v[212:215], v[30:33]
	v_mfma_f32_16x16x32_bf16 v[22:25], v[150:153], v[220:223], v[22:25]
	v_mfma_f32_16x16x32_bf16 v[14:17], v[158:161], v[220:223], v[14:17]
	s_setprio 0
	s_setprio 1
	s_add_i32 s73, s73, 2
	s_add_u32 s71, s71, 0x10000
	s_addc_u32 s72, s72, 0
	s_add_u32 s54, s54, 0x100
	s_addc_u32 s55, s55, 0
	s_cmp_gt_u32 s73, 29
	s_setprio 0
	s_barrier
	s_cbranch_scc0 .Lgi_h0_loop
	s_branch .Lgi_after_loop
.Lgi_h1_loop:
	s_add_i32 s12, 0, 0x10000
	s_add_i32 s13, 0, 0x14000
	v_add_u32_e32 v158, s12, v147
	v_add_u32_e32 v174, s13, v147
	ds_read_b128 v[162:165], v174
	ds_read_b128 v[166:169], v174 offset:1024
	ds_read_b128 v[170:173], v174 offset:2048
	ds_read_b128 v[174:177], v174 offset:3072
	v_lshl_add_u64 v[194:195], s[54:55], 0, v[138:139]
	s_add_i32 m0, s59, 0xc000
	ds_read_b128 v[178:181], v149
	ds_read_b128 v[182:185], v149 offset:1024
	ds_read_b128 v[186:189], v149 offset:2048
	ds_read_b128 v[190:193], v149 offset:3072
	ds_read_b128 v[208:211], v149 offset:4096
	ds_read_b128 v[212:215], v149 offset:5120
	ds_read_b128 v[216:219], v149 offset:6144
	ds_read_b128 v[220:223], v149 offset:7168
	s_add_u32 s10, s54, 0xfff80080
	s_addc_u32 s11, s55, -1
	s_cmp_eq_u32 s73, 28
	s_cselect_b32 s57, s45, s11
	s_cselect_b32 s56, s69, s10
	s_cselect_b32 s21, s43, s72
	s_cselect_b32 s20, s70, s71
	global_load_lds_dwordx4 v[194:195], off
	v_lshl_add_u64 v[194:195], s[54:55], 0, v[140:141]
	s_add_i32 m0, s59, 0xe000
	s_nop 0
	global_load_lds_dwordx4 v[194:195], off
	s_waitcnt vmcnt(8)
	s_waitcnt lgkmcnt(0)
	s_barrier
	s_setprio 1
	s_waitcnt lgkmcnt(0)
	s_setprio 0
	s_setprio 1
	v_mfma_f32_16x16x32_bf16 v[116:119], v[162:165], v[178:181], v[116:119]
	v_mfma_f32_16x16x32_bf16 v[108:111], v[170:173], v[178:181], v[108:111]
	v_mfma_f32_16x16x32_bf16 v[100:103], v[162:165], v[186:189], v[100:103]
	v_mfma_f32_16x16x32_bf16 v[90:93], v[170:173], v[186:189], v[90:93]
	v_mfma_f32_16x16x32_bf16 v[82:85], v[162:165], v[208:211], v[82:85]
	v_mfma_f32_16x16x32_bf16 v[74:77], v[170:173], v[208:211], v[74:77]
	v_mfma_f32_16x16x32_bf16 v[70:73], v[162:165], v[216:219], v[70:73]
	v_mfma_f32_16x16x32_bf16 v[66:69], v[170:173], v[216:219], v[66:69]
	v_mfma_f32_16x16x32_bf16 v[116:119], v[166:169], v[182:185], v[116:119]
	v_mfma_f32_16x16x32_bf16 v[108:111], v[174:177], v[182:185], v[108:111]
	v_mfma_f32_16x16x32_bf16 v[100:103], v[166:169], v[190:193], v[100:103]
	v_mfma_f32_16x16x32_bf16 v[90:93], v[174:177], v[190:193], v[90:93]
	v_mfma_f32_16x16x32_bf16 v[82:85], v[166:169], v[212:215], v[82:85]
	v_mfma_f32_16x16x32_bf16 v[74:77], v[174:177], v[212:215], v[74:77]
	v_mfma_f32_16x16x32_bf16 v[70:73], v[166:169], v[220:223], v[70:73]
	v_mfma_f32_16x16x32_bf16 v[66:69], v[174:177], v[220:223], v[66:69]
	s_setprio 0
	s_barrier
	s_add_i32 s10, s12, s58
	v_lshl_add_u64 v[194:195], s[20:21], 0, v[136:137]
	s_mov_b32 m0, s10
	ds_read_b128 v[178:181], v149 offset:16384
	ds_read_b128 v[182:185], v149 offset:17408
	ds_read_b128 v[186:189], v149 offset:18432
	ds_read_b128 v[190:193], v149 offset:19456
	ds_read_b128 v[208:211], v149 offset:20480
	ds_read_b128 v[212:215], v149 offset:21504
	ds_read_b128 v[216:219], v149 offset:22528
	ds_read_b128 v[220:223], v149 offset:23552
	global_load_lds_dwordx4 v[194:195], off
	s_add_i32 m0, s10, 0x2000
	s_add_u32 s10, s20, 0x4000
	v_lshl_add_u64 v[194:195], s[20:21], 0, v[132:133]
	s_addc_u32 s11, s21, 0
	s_add_i32 s12, s13, s58
	global_load_lds_dwordx4 v[194:195], off
	v_lshl_add_u64 v[194:195], s[10:11], 0, v[136:137]
	s_mov_b32 m0, s12
	v_lshl_add_u64 v[196:197], s[56:57], 0, v[134:135]
	global_load_lds_dwordx4 v[194:195], off
	v_lshl_add_u64 v[194:195], s[10:11], 0, v[132:133]
	s_add_i32 m0, s12, 0x2000
	s_nop 0
	global_load_lds_dwordx4 v[194:195], off
	v_lshl_add_u64 v[194:195], s[56:57], 0, v[98:99]
	s_mov_b32 m0, s59
	s_nop 0
	global_load_lds_dwordx4 v[194:195], off
	s_mov_b32 m0, s60
	s_nop 0
	global_load_lds_dwordx4 v[196:197], off
	s_waitcnt vmcnt(8)
	s_waitcnt lgkmcnt(0)
	s_barrier
	s_setprio 1
	s_waitcnt lgkmcnt(0)
	s_setprio 0
	s_setprio 1
	v_mfma_f32_16x16x32_bf16 v[50:53], v[162:165], v[178:181], v[50:53]
	v_mfma_f32_16x16x32_bf16 v[42:45], v[170:173], v[178:181], v[42:45]
	v_mfma_f32_16x16x32_bf16 v[34:37], v[162:165], v[186:189], v[34:37]
	v_mfma_f32_16x16x32_bf16 v[26:29], v[170:173], v[186:189], v[26:29]
	v_mfma_f32_16x16x32_bf16 v[18:21], v[162:165], v[208:211], v[18:21]
	v_mfma_f32_16x16x32_bf16 v[10:13], v[170:173], v[208:211], v[10:13]
	v_mfma_f32_16x16x32_bf16 v[6:9], v[162:165], v[216:219], v[6:9]
	v_mfma_f32_16x16x32_bf16 v[2:5], v[170:173], v[216:219], v[2:5]
	v_mfma_f32_16x16x32_bf16 v[50:53], v[166:169], v[182:185], v[50:53]
	v_mfma_f32_16x16x32_bf16 v[42:45], v[174:177], v[182:185], v[42:45]
	v_mfma_f32_16x16x32_bf16 v[34:37], v[166:169], v[190:193], v[34:37]
	v_mfma_f32_16x16x32_bf16 v[26:29], v[174:177], v[190:193], v[26:29]
	v_mfma_f32_16x16x32_bf16 v[18:21], v[166:169], v[212:215], v[18:21]
	v_mfma_f32_16x16x32_bf16 v[10:13], v[174:177], v[212:215], v[10:13]
	v_mfma_f32_16x16x32_bf16 v[6:9], v[166:169], v[220:223], v[6:9]
	v_mfma_f32_16x16x32_bf16 v[2:5], v[174:177], v[220:223], v[2:5]
	s_setprio 0
	s_barrier
	s_add_i32 s12, 0, 0x18000
	s_add_i32 s13, 0, 0x1c000
	v_add_u32_e32 v158, s12, v147
	v_add_u32_e32 v174, s13, v147
	ds_read_b128 v[162:165], v174
	ds_read_b128 v[166:169], v174 offset:1024
	ds_read_b128 v[170:173], v174 offset:2048
	ds_read_b128 v[174:177], v174 offset:3072
	s_add_u32 s10, s56, 0x80000
	s_addc_u32 s11, s57, 0
	s_mov_b32 m0, s61
	v_lshl_add_u64 v[198:199], s[10:11], 0, v[98:99]
	ds_read_b128 v[178:181], v149 offset:32768
	ds_read_b128 v[182:185], v149 offset:33792
	ds_read_b128 v[186:189], v149 offset:34816
	ds_read_b128 v[190:193], v149 offset:35840
	ds_read_b128 v[208:211], v149 offset:36864
	ds_read_b128 v[212:215], v149 offset:37888
	ds_read_b128 v[216:219], v149 offset:38912
	ds_read_b128 v[220:223], v149 offset:39936
	global_load_lds_dwordx4 v[198:199], off
	v_lshl_add_u64 v[198:199], s[10:11], 0, v[134:135]
	s_mov_b32 m0, s62
	s_nop 0
	global_load_lds_dwordx4 v[198:199], off
	s_waitcnt vmcnt(8)
	s_waitcnt lgkmcnt(0)
	s_barrier
	s_setprio 1
	s_waitcnt lgkmcnt(0)
	s_setprio 0
	s_setprio 1
	v_mfma_f32_16x16x32_bf16 v[116:119], v[162:165], v[178:181], v[116:119]
	v_mfma_f32_16x16x32_bf16 v[108:111], v[170:173], v[178:181], v[108:111]
	v_mfma_f32_16x16x32_bf16 v[100:103], v[162:165], v[186:189], v[100:103]
	v_mfma_f32_16x16x32_bf16 v[90:93], v[170:173], v[186:189], v[90:93]
	v_mfma_f32_16x16x32_bf16 v[82:85], v[162:165], v[208:211], v[82:85]
	v_mfma_f32_16x16x32_bf16 v[74:77], v[170:173], v[208:211], v[74:77]
	v_mfma_f32_16x16x32_bf16 v[70:73], v[162:165], v[216:219], v[70:73]
	v_mfma_f32_16x16x32_bf16 v[66:69], v[170:173], v[216:219], v[66:69]
	v_mfma_f32_16x16x32_bf16 v[116:119], v[166:169], v[182:185], v[116:119]
	v_mfma_f32_16x16x32_bf16 v[108:111], v[174:177], v[182:185], v[108:111]
	v_mfma_f32_16x16x32_bf16 v[100:103], v[166:169], v[190:193], v[100:103]
	v_mfma_f32_16x16x32_bf16 v[90:93], v[174:177], v[190:193], v[90:93]
	v_mfma_f32_16x16x32_bf16 v[82:85], v[166:169], v[212:215], v[82:85]
	v_mfma_f32_16x16x32_bf16 v[74:77], v[174:177], v[212:215], v[74:77]
	v_mfma_f32_16x16x32_bf16 v[70:73], v[166:169], v[220:223], v[70:73]
	v_mfma_f32_16x16x32_bf16 v[66:69], v[174:177], v[220:223], v[66:69]
	s_setprio 0
	s_barrier
	s_add_u32 s10, s20, 0x8000
	s_addc_u32 s11, s21, 0
	s_add_i32 s12, s12, s58
	v_lshl_add_u64 v[198:199], s[10:11], 0, v[136:137]
	s_mov_b32 m0, s12
	ds_read_b128 v[178:181], v149 offset:49152
	ds_read_b128 v[182:185], v149 offset:50176
	ds_read_b128 v[186:189], v149 offset:51200
	ds_read_b128 v[190:193], v149 offset:52224
	ds_read_b128 v[208:211], v149 offset:53248
	ds_read_b128 v[212:215], v149 offset:54272
	ds_read_b128 v[216:219], v149 offset:55296
	ds_read_b128 v[220:223], v149 offset:56320
	global_load_lds_dwordx4 v[198:199], off
	s_add_i32 m0, s12, 0x2000
	v_lshl_add_u64 v[198:199], s[10:11], 0, v[132:133]
	s_add_u32 s10, s20, 0xc000
	s_addc_u32 s11, s21, 0
	s_add_i32 s12, s13, s58
	global_load_lds_dwordx4 v[198:199], off
	v_lshl_add_u64 v[198:199], s[10:11], 0, v[136:137]
	s_mov_b32 m0, s12
	v_lshl_add_u64 v[194:195], v[194:195], 0, s[24:25]
	global_load_lds_dwordx4 v[198:199], off
	v_lshl_add_u64 v[198:199], s[10:11], 0, v[132:133]
	s_add_i32 m0, s12, 0x2000
	s_nop 0
	global_load_lds_dwordx4 v[198:199], off
	s_mov_b32 m0, s63
	s_nop 0
	global_load_lds_dwordx4 v[194:195], off
	v_lshl_add_u64 v[194:195], v[196:197], 0, s[24:25]
	s_mov_b32 m0, s64
	s_nop 0
	global_load_lds_dwordx4 v[194:195], off
	s_waitcnt vmcnt(8)
	s_waitcnt lgkmcnt(0)
	s_barrier
	s_setprio 1
	s_waitcnt lgkmcnt(0)
	s_setprio 0
	s_setprio 1
	v_mfma_f32_16x16x32_bf16 v[50:53], v[162:165], v[178:181], v[50:53]
	v_mfma_f32_16x16x32_bf16 v[42:45], v[170:173], v[178:181], v[42:45]
	v_mfma_f32_16x16x32_bf16 v[34:37], v[162:165], v[186:189], v[34:37]
	v_mfma_f32_16x16x32_bf16 v[26:29], v[170:173], v[186:189], v[26:29]
	v_mfma_f32_16x16x32_bf16 v[18:21], v[162:165], v[208:211], v[18:21]
	v_mfma_f32_16x16x32_bf16 v[10:13], v[170:173], v[208:211], v[10:13]
	v_mfma_f32_16x16x32_bf16 v[6:9], v[162:165], v[216:219], v[6:9]
	v_mfma_f32_16x16x32_bf16 v[2:5], v[170:173], v[216:219], v[2:5]
	v_mfma_f32_16x16x32_bf16 v[50:53], v[166:169], v[182:185], v[50:53]
	v_mfma_f32_16x16x32_bf16 v[42:45], v[174:177], v[182:185], v[42:45]
	v_mfma_f32_16x16x32_bf16 v[34:37], v[166:169], v[190:193], v[34:37]
	v_mfma_f32_16x16x32_bf16 v[26:29], v[174:177], v[190:193], v[26:29]
	v_mfma_f32_16x16x32_bf16 v[18:21], v[166:169], v[212:215], v[18:21]
	v_mfma_f32_16x16x32_bf16 v[10:13], v[174:177], v[212:215], v[10:13]
	v_mfma_f32_16x16x32_bf16 v[6:9], v[166:169], v[220:223], v[6:9]
	v_mfma_f32_16x16x32_bf16 v[2:5], v[174:177], v[220:223], v[2:5]
	s_add_i32 s73, s73, 2
	s_add_u32 s71, s71, 0x10000
	s_addc_u32 s72, s72, 0
	s_add_u32 s54, s54, 0x100
	s_addc_u32 s55, s55, 0
	s_cmp_gt_u32 s73, 29
	s_setprio 0
	s_barrier
	s_cbranch_scc0 .Lgi_h1_loop
	s_branch .Lgi_after_loop

.LBB0_976:
	s_add_i32 s11, 0, 0x10000
	s_add_i32 s14, 0, 0x14000
	v_add_u32_e32 v140, s11, v234
	v_add_u32_e32 v156, s14, v234
	ds_read_b128 v[120:123], v140
	ds_read_b128 v[128:131], v140 offset:1024
	ds_read_b128 v[136:139], v140 offset:2048
	ds_read_b128 v[140:143], v140 offset:3072
	ds_read_b128 v[144:147], v156
	ds_read_b128 v[148:151], v156 offset:1024
	ds_read_b128 v[152:155], v156 offset:2048
	ds_read_b128 v[156:159], v156 offset:3072
	v_lshl_add_u64 v[196:197], s[48:49], 0, v[220:221]
	s_add_i32 m0, s37, 0xc000
	ds_read_b128 v[164:167], v238
	ds_read_b128 v[168:171], v238 offset:1024
	ds_read_b128 v[172:175], v238 offset:2048
	ds_read_b128 v[176:179], v238 offset:3072
	ds_read_b128 v[180:183], v238 offset:4096
	ds_read_b128 v[184:187], v238 offset:5120
	ds_read_b128 v[188:191], v238 offset:6144
	ds_read_b128 v[192:195], v238 offset:7168
	s_add_u32 s4, s48, 0xfff80080
	s_addc_u32 s5, s49, -1
	s_cmp_eq_u32 s10, 28
	s_cselect_b32 vcc_hi, s9, s5
	s_cselect_b32 vcc_lo, s47, s4
	s_cselect_b32 s5, s71, s77
	s_cselect_b32 s4, s73, s76
	global_load_lds_dwordx4 v[196:197], off
	v_lshl_add_u64 v[196:197], s[48:49], 0, v[218:219]
	s_add_i32 m0, s37, 0xe000
	s_nop 0
	global_load_lds_dwordx4 v[196:197], off
	s_waitcnt vmcnt(8)
	s_waitcnt lgkmcnt(0)
	s_barrier
	s_setprio 1
	s_waitcnt lgkmcnt(0)
	v_mfma_f32_16x16x32_bf16 v[108:111], v[120:123], v[164:167], v[108:111]
	v_mfma_f32_16x16x32_bf16 v[104:107], v[136:139], v[164:167], v[104:107]
	v_mfma_f32_16x16x32_bf16 v[112:115], v[120:123], v[172:175], v[112:115]
	v_mfma_f32_16x16x32_bf16 v[100:103], v[136:139], v[172:175], v[100:103]
	v_mfma_f32_16x16x32_bf16 v[86:89], v[120:123], v[180:183], v[86:89]
	v_mfma_f32_16x16x32_bf16 v[82:85], v[136:139], v[180:183], v[82:85]
	v_mfma_f32_16x16x32_bf16 v[74:77], v[120:123], v[188:191], v[74:77]
	v_mfma_f32_16x16x32_bf16 v[66:69], v[136:139], v[188:191], v[66:69]
	v_mfma_f32_16x16x32_bf16 v[108:111], v[128:131], v[168:171], v[108:111]
	v_mfma_f32_16x16x32_bf16 v[104:107], v[140:143], v[168:171], v[104:107]
	v_mfma_f32_16x16x32_bf16 v[112:115], v[128:131], v[176:179], v[112:115]
	v_mfma_f32_16x16x32_bf16 v[100:103], v[140:143], v[176:179], v[100:103]
	v_mfma_f32_16x16x32_bf16 v[86:89], v[128:131], v[184:187], v[86:89]
	v_mfma_f32_16x16x32_bf16 v[82:85], v[140:143], v[184:187], v[82:85]
	v_mfma_f32_16x16x32_bf16 v[74:77], v[128:131], v[192:195], v[74:77]
	v_mfma_f32_16x16x32_bf16 v[66:69], v[140:143], v[192:195], v[66:69]
	s_setprio 0
	s_setprio 1
	v_mfma_f32_16x16x32_bf16 v[160:163], v[144:147], v[164:167], v[160:163]
	v_mfma_f32_16x16x32_bf16 v[132:135], v[152:155], v[164:167], v[132:135]
	v_mfma_f32_16x16x32_bf16 v[124:127], v[144:147], v[172:175], v[124:127]
	v_mfma_f32_16x16x32_bf16 v[116:119], v[152:155], v[172:175], v[116:119]
	v_mfma_f32_16x16x32_bf16 v[94:97], v[144:147], v[180:183], v[94:97]
	v_mfma_f32_16x16x32_bf16 v[90:93], v[152:155], v[180:183], v[90:93]
	v_mfma_f32_16x16x32_bf16 v[78:81], v[144:147], v[188:191], v[78:81]
	v_mfma_f32_16x16x32_bf16 v[70:73], v[152:155], v[188:191], v[70:73]
	v_mfma_f32_16x16x32_bf16 v[160:163], v[148:151], v[168:171], v[160:163]
	v_mfma_f32_16x16x32_bf16 v[132:135], v[156:159], v[168:171], v[132:135]
	v_mfma_f32_16x16x32_bf16 v[124:127], v[148:151], v[176:179], v[124:127]
	v_mfma_f32_16x16x32_bf16 v[116:119], v[156:159], v[176:179], v[116:119]
	v_mfma_f32_16x16x32_bf16 v[94:97], v[148:151], v[184:187], v[94:97]
	v_mfma_f32_16x16x32_bf16 v[90:93], v[156:159], v[184:187], v[90:93]
	v_mfma_f32_16x16x32_bf16 v[78:81], v[148:151], v[192:195], v[78:81]
	v_mfma_f32_16x16x32_bf16 v[70:73], v[156:159], v[192:195], v[70:73]
	s_setprio 0
	s_barrier
	s_add_i32 s11, s11, s88
	v_lshl_add_u64 v[196:197], s[4:5], 0, v[210:211]
	s_mov_b32 m0, s11
	ds_read_b128 v[164:167], v238 offset:16384
	ds_read_b128 v[168:171], v238 offset:17408
	ds_read_b128 v[172:175], v238 offset:18432
	ds_read_b128 v[176:179], v238 offset:19456
	ds_read_b128 v[180:183], v238 offset:20480
	ds_read_b128 v[184:187], v238 offset:21504
	ds_read_b128 v[188:191], v238 offset:22528
	ds_read_b128 v[192:195], v238 offset:23552
	global_load_lds_dwordx4 v[196:197], off
	s_add_i32 m0, s11, 0x2000
	s_add_u32 s12, s4, 0x4000
	v_lshl_add_u64 v[196:197], s[4:5], 0, v[214:215]
	s_addc_u32 s13, s5, 0
	s_add_i32 s11, s14, s88
	global_load_lds_dwordx4 v[196:197], off
	v_lshl_add_u64 v[196:197], s[12:13], 0, v[210:211]
	s_mov_b32 m0, s11
	v_lshl_add_u64 v[198:199], vcc, 0, v[212:213]
	global_load_lds_dwordx4 v[196:197], off
	v_lshl_add_u64 v[196:197], s[12:13], 0, v[214:215]
	s_add_i32 m0, s11, 0x2000
	s_nop 0
	global_load_lds_dwordx4 v[196:197], off
	v_lshl_add_u64 v[196:197], vcc, 0, v[208:209]
	s_mov_b32 m0, s37
	s_nop 0
	global_load_lds_dwordx4 v[196:197], off
	s_mov_b32 m0, s89
	s_nop 0
	global_load_lds_dwordx4 v[198:199], off
	s_waitcnt vmcnt(8)
	s_waitcnt lgkmcnt(0)
	s_barrier
	s_setprio 1
	s_waitcnt lgkmcnt(0)
	v_mfma_f32_16x16x32_bf16 v[54:57], v[120:123], v[164:167], v[54:57]
	v_mfma_f32_16x16x32_bf16 v[50:53], v[136:139], v[164:167], v[50:53]
	v_mfma_f32_16x16x32_bf16 v[38:41], v[120:123], v[172:175], v[38:41]
	v_mfma_f32_16x16x32_bf16 v[34:37], v[136:139], v[172:175], v[34:37]
	v_mfma_f32_16x16x32_bf16 v[22:25], v[120:123], v[180:183], v[22:25]
	v_mfma_f32_16x16x32_bf16 v[18:21], v[136:139], v[180:183], v[18:21]
	v_mfma_f32_16x16x32_bf16 v[14:17], v[120:123], v[188:191], v[14:17]
	v_mfma_f32_16x16x32_bf16 v[10:13], v[136:139], v[188:191], v[10:13]
	v_mfma_f32_16x16x32_bf16 v[54:57], v[128:131], v[168:171], v[54:57]
	v_mfma_f32_16x16x32_bf16 v[50:53], v[140:143], v[168:171], v[50:53]
	v_mfma_f32_16x16x32_bf16 v[38:41], v[128:131], v[176:179], v[38:41]
	v_mfma_f32_16x16x32_bf16 v[34:37], v[140:143], v[176:179], v[34:37]
	v_mfma_f32_16x16x32_bf16 v[22:25], v[128:131], v[184:187], v[22:25]
	v_mfma_f32_16x16x32_bf16 v[18:21], v[140:143], v[184:187], v[18:21]
	v_mfma_f32_16x16x32_bf16 v[14:17], v[128:131], v[192:195], v[14:17]
	v_mfma_f32_16x16x32_bf16 v[10:13], v[140:143], v[192:195], v[10:13]
	s_setprio 0
	s_setprio 1
	v_mfma_f32_16x16x32_bf16 v[62:65], v[144:147], v[164:167], v[62:65]
	v_mfma_f32_16x16x32_bf16 v[58:61], v[152:155], v[164:167], v[58:61]
	v_mfma_f32_16x16x32_bf16 v[46:49], v[144:147], v[172:175], v[46:49]
	v_mfma_f32_16x16x32_bf16 v[42:45], v[152:155], v[172:175], v[42:45]
	v_mfma_f32_16x16x32_bf16 v[30:33], v[144:147], v[180:183], v[30:33]
	v_mfma_f32_16x16x32_bf16 v[26:29], v[152:155], v[180:183], v[26:29]
	v_mfma_f32_16x16x32_bf16 v[6:9], v[144:147], v[188:191], v[6:9]
	v_mfma_f32_16x16x32_bf16 v[2:5], v[152:155], v[188:191], v[2:5]
	v_mfma_f32_16x16x32_bf16 v[62:65], v[148:151], v[168:171], v[62:65]
	v_mfma_f32_16x16x32_bf16 v[58:61], v[156:159], v[168:171], v[58:61]
	v_mfma_f32_16x16x32_bf16 v[46:49], v[148:151], v[176:179], v[46:49]
	v_mfma_f32_16x16x32_bf16 v[42:45], v[156:159], v[176:179], v[42:45]
	v_mfma_f32_16x16x32_bf16 v[30:33], v[148:151], v[184:187], v[30:33]
	v_mfma_f32_16x16x32_bf16 v[26:29], v[156:159], v[184:187], v[26:29]
	v_mfma_f32_16x16x32_bf16 v[6:9], v[148:151], v[192:195], v[6:9]
	v_mfma_f32_16x16x32_bf16 v[2:5], v[156:159], v[192:195], v[2:5]
	s_setprio 0
	s_barrier
	s_add_i32 s11, 0, 0x18000
	s_add_i32 s14, 0, 0x1c000
	v_add_u32_e32 v140, s11, v234
	v_add_u32_e32 v156, s14, v234
	ds_read_b128 v[120:123], v140
	ds_read_b128 v[128:131], v140 offset:1024
	ds_read_b128 v[136:139], v140 offset:2048
	ds_read_b128 v[140:143], v140 offset:3072
	ds_read_b128 v[144:147], v156
	ds_read_b128 v[148:151], v156 offset:1024
	ds_read_b128 v[152:155], v156 offset:2048
	ds_read_b128 v[156:159], v156 offset:3072
	s_add_u32 s12, vcc_lo, 0x80000
	s_addc_u32 s13, vcc_hi, 0
	s_mov_b32 m0, s90
	v_lshl_add_u64 v[222:223], s[12:13], 0, v[208:209]
	ds_read_b128 v[164:167], v238 offset:32768
	ds_read_b128 v[168:171], v238 offset:33792
	ds_read_b128 v[172:175], v238 offset:34816
	ds_read_b128 v[176:179], v238 offset:35840
	ds_read_b128 v[180:183], v238 offset:36864
	ds_read_b128 v[184:187], v238 offset:37888
	ds_read_b128 v[188:191], v238 offset:38912
	ds_read_b128 v[192:195], v238 offset:39936
	global_load_lds_dwordx4 v[222:223], off
	v_lshl_add_u64 v[222:223], s[12:13], 0, v[212:213]
	s_mov_b32 m0, s91
	s_nop 0
	global_load_lds_dwordx4 v[222:223], off
	s_waitcnt vmcnt(8)
	s_waitcnt lgkmcnt(0)
	s_barrier
	s_setprio 1
	s_waitcnt lgkmcnt(0)
	v_mfma_f32_16x16x32_bf16 v[108:111], v[120:123], v[164:167], v[108:111]
	v_mfma_f32_16x16x32_bf16 v[104:107], v[136:139], v[164:167], v[104:107]
	v_mfma_f32_16x16x32_bf16 v[112:115], v[120:123], v[172:175], v[112:115]
	v_mfma_f32_16x16x32_bf16 v[100:103], v[136:139], v[172:175], v[100:103]
	v_mfma_f32_16x16x32_bf16 v[86:89], v[120:123], v[180:183], v[86:89]
	v_mfma_f32_16x16x32_bf16 v[82:85], v[136:139], v[180:183], v[82:85]
	v_mfma_f32_16x16x32_bf16 v[74:77], v[120:123], v[188:191], v[74:77]
	v_mfma_f32_16x16x32_bf16 v[66:69], v[136:139], v[188:191], v[66:69]
	v_mfma_f32_16x16x32_bf16 v[108:111], v[128:131], v[168:171], v[108:111]
	v_mfma_f32_16x16x32_bf16 v[104:107], v[140:143], v[168:171], v[104:107]
	v_mfma_f32_16x16x32_bf16 v[112:115], v[128:131], v[176:179], v[112:115]
	v_mfma_f32_16x16x32_bf16 v[100:103], v[140:143], v[176:179], v[100:103]
	v_mfma_f32_16x16x32_bf16 v[86:89], v[128:131], v[184:187], v[86:89]
	v_mfma_f32_16x16x32_bf16 v[82:85], v[140:143], v[184:187], v[82:85]
	v_mfma_f32_16x16x32_bf16 v[74:77], v[128:131], v[192:195], v[74:77]
	v_mfma_f32_16x16x32_bf16 v[66:69], v[140:143], v[192:195], v[66:69]
	s_setprio 0
	s_setprio 1
	v_mfma_f32_16x16x32_bf16 v[160:163], v[144:147], v[164:167], v[160:163]
	v_mfma_f32_16x16x32_bf16 v[132:135], v[152:155], v[164:167], v[132:135]
	v_mfma_f32_16x16x32_bf16 v[124:127], v[144:147], v[172:175], v[124:127]
	v_mfma_f32_16x16x32_bf16 v[116:119], v[152:155], v[172:175], v[116:119]
	v_mfma_f32_16x16x32_bf16 v[94:97], v[144:147], v[180:183], v[94:97]
	v_mfma_f32_16x16x32_bf16 v[90:93], v[152:155], v[180:183], v[90:93]
	v_mfma_f32_16x16x32_bf16 v[78:81], v[144:147], v[188:191], v[78:81]
	v_mfma_f32_16x16x32_bf16 v[70:73], v[152:155], v[188:191], v[70:73]
	v_mfma_f32_16x16x32_bf16 v[160:163], v[148:151], v[168:171], v[160:163]
	v_mfma_f32_16x16x32_bf16 v[132:135], v[156:159], v[168:171], v[132:135]
	v_mfma_f32_16x16x32_bf16 v[124:127], v[148:151], v[176:179], v[124:127]
	v_mfma_f32_16x16x32_bf16 v[116:119], v[156:159], v[176:179], v[116:119]
	v_mfma_f32_16x16x32_bf16 v[94:97], v[148:151], v[184:187], v[94:97]
	v_mfma_f32_16x16x32_bf16 v[90:93], v[156:159], v[184:187], v[90:93]
	v_mfma_f32_16x16x32_bf16 v[78:81], v[148:151], v[192:195], v[78:81]
	v_mfma_f32_16x16x32_bf16 v[70:73], v[156:159], v[192:195], v[70:73]
	s_setprio 0
	s_barrier
	s_add_u32 s12, s4, 0x8000
	s_addc_u32 s13, s5, 0
	s_add_i32 s11, s11, s88
	v_lshl_add_u64 v[222:223], s[12:13], 0, v[210:211]
	s_mov_b32 m0, s11
	ds_read_b128 v[164:167], v238 offset:49152
	ds_read_b128 v[168:171], v238 offset:50176
	ds_read_b128 v[172:175], v238 offset:51200
	ds_read_b128 v[176:179], v238 offset:52224
	ds_read_b128 v[180:183], v238 offset:53248
	ds_read_b128 v[184:187], v238 offset:54272
	ds_read_b128 v[188:191], v238 offset:55296
	ds_read_b128 v[192:195], v238 offset:56320
	global_load_lds_dwordx4 v[222:223], off
	s_add_i32 m0, s11, 0x2000
	s_add_u32 s4, s4, 0xc000
	v_lshl_add_u64 v[222:223], s[12:13], 0, v[214:215]
	s_addc_u32 s5, s5, 0
	s_add_i32 s11, s14, s88
	global_load_lds_dwordx4 v[222:223], off
	v_lshl_add_u64 v[222:223], s[4:5], 0, v[210:211]
	s_mov_b32 m0, s11
	v_lshl_add_u64 v[196:197], v[196:197], 0, s[24:25]
	global_load_lds_dwordx4 v[222:223], off
	v_lshl_add_u64 v[222:223], s[4:5], 0, v[214:215]
	s_add_i32 m0, s11, 0x2000
	s_nop 0
	global_load_lds_dwordx4 v[222:223], off
	s_mov_b32 m0, s94
	s_nop 0
	global_load_lds_dwordx4 v[196:197], off
	v_lshl_add_u64 v[196:197], v[198:199], 0, s[24:25]
	s_mov_b32 m0, s95
	s_nop 0
	global_load_lds_dwordx4 v[196:197], off
	s_waitcnt vmcnt(8)
	s_waitcnt lgkmcnt(0)
	s_barrier
	s_setprio 1
	s_waitcnt lgkmcnt(0)
	v_mfma_f32_16x16x32_bf16 v[54:57], v[120:123], v[164:167], v[54:57]
	v_mfma_f32_16x16x32_bf16 v[50:53], v[136:139], v[164:167], v[50:53]
	v_mfma_f32_16x16x32_bf16 v[38:41], v[120:123], v[172:175], v[38:41]
	v_mfma_f32_16x16x32_bf16 v[34:37], v[136:139], v[172:175], v[34:37]
	v_mfma_f32_16x16x32_bf16 v[22:25], v[120:123], v[180:183], v[22:25]
	v_mfma_f32_16x16x32_bf16 v[18:21], v[136:139], v[180:183], v[18:21]
	v_mfma_f32_16x16x32_bf16 v[14:17], v[120:123], v[188:191], v[14:17]
	v_mfma_f32_16x16x32_bf16 v[10:13], v[136:139], v[188:191], v[10:13]
	v_mfma_f32_16x16x32_bf16 v[54:57], v[128:131], v[168:171], v[54:57]
	v_mfma_f32_16x16x32_bf16 v[50:53], v[140:143], v[168:171], v[50:53]
	v_mfma_f32_16x16x32_bf16 v[38:41], v[128:131], v[176:179], v[38:41]
	v_mfma_f32_16x16x32_bf16 v[34:37], v[140:143], v[176:179], v[34:37]
	v_mfma_f32_16x16x32_bf16 v[22:25], v[128:131], v[184:187], v[22:25]
	v_mfma_f32_16x16x32_bf16 v[18:21], v[140:143], v[184:187], v[18:21]
	v_mfma_f32_16x16x32_bf16 v[14:17], v[128:131], v[192:195], v[14:17]
	v_mfma_f32_16x16x32_bf16 v[10:13], v[140:143], v[192:195], v[10:13]
	s_setprio 0
	s_setprio 1
	v_mfma_f32_16x16x32_bf16 v[62:65], v[144:147], v[164:167], v[62:65]
	v_mfma_f32_16x16x32_bf16 v[58:61], v[152:155], v[164:167], v[58:61]
	v_mfma_f32_16x16x32_bf16 v[46:49], v[144:147], v[172:175], v[46:49]
	v_mfma_f32_16x16x32_bf16 v[42:45], v[152:155], v[172:175], v[42:45]
	v_mfma_f32_16x16x32_bf16 v[30:33], v[144:147], v[180:183], v[30:33]
	v_mfma_f32_16x16x32_bf16 v[26:29], v[152:155], v[180:183], v[26:29]
	v_mfma_f32_16x16x32_bf16 v[6:9], v[144:147], v[188:191], v[6:9]
	v_mfma_f32_16x16x32_bf16 v[2:5], v[152:155], v[188:191], v[2:5]
	v_mfma_f32_16x16x32_bf16 v[62:65], v[148:151], v[168:171], v[62:65]
	v_mfma_f32_16x16x32_bf16 v[58:61], v[156:159], v[168:171], v[58:61]
	v_mfma_f32_16x16x32_bf16 v[46:49], v[148:151], v[176:179], v[46:49]
	v_mfma_f32_16x16x32_bf16 v[42:45], v[156:159], v[176:179], v[42:45]
	v_mfma_f32_16x16x32_bf16 v[30:33], v[148:151], v[184:187], v[30:33]
	v_mfma_f32_16x16x32_bf16 v[26:29], v[156:159], v[184:187], v[26:29]
	v_mfma_f32_16x16x32_bf16 v[6:9], v[148:151], v[192:195], v[6:9]
	v_mfma_f32_16x16x32_bf16 v[2:5], v[156:159], v[192:195], v[2:5]
	s_add_i32 s10, s10, 2
	s_add_u32 s76, s76, 0x10000
	s_addc_u32 s77, s77, 0
	s_add_u32 s48, s48, 0x100
	s_addc_u32 s49, s49, 0
	s_cmp_gt_u32 s10, 29
	s_setprio 0
	s_barrier
	s_cbranch_scc0 .LBB0_976
	s_and_b64 vcc, exec, s[60:61]
	s_cbranch_vccz .LBB0_979
	s_barrier
